# plus MLA tile loop issues the next K/V tile's global loads before the end-of-tile barrier (right after the LDS stores that free the staging registers) instead of after it
# speedup vs baseline: 1.0002x; 1.0002x over previous
.LBB0_2638:
	s_add_i32 s64, s64, 64
	s_cmp_lt_i32 s65, s43
	s_cbranch_scc0 .Lmla_nopf
	s_add_i32 s6, s64, 64
	s_lshl_b64 s[60:61], s[6:7], 13
	s_lshl_b64 s[66:67], s[6:7], 7
	v_lshl_add_u64 v[2:3], v[188:189], 0, s[60:61]
	v_add_co_u32_e32 v4, vcc, 0x40000, v2
	v_lshl_add_u64 v[6:7], v[190:191], 0, s[66:67]
	s_nop 0
	v_addc_co_u32_e32 v5, vcc, 0, v3, vcc
	global_load_dwordx4 v[164:167], v[6:7], off
	global_load_dwordx4 v[160:163], v[2:3], off
	global_load_dwordx4 v[172:175], v[2:3], off offset:256
	global_load_dwordx4 v[168:171], v[4:5], off
	global_load_dwordx4 v[176:179], v[4:5], off offset:256
.Lmla_nopf:
	s_cmp_lg_u32 s57, s65
	s_waitcnt lgkmcnt(0)
	s_barrier
	s_cbranch_scc0 .LBB0_2618
	v_mov_b32_e32 v207, v15
	s_cmp_lt_i32 s65, s43
	s_cselect_b64 s[16:17], -1, 0
	s_branch .LBB0_2630
